# EpiRes (P8, P4 layer0): second-half residual loads hoisted before first-half stores; second half no longer waits for store drain
# baseline (speedup 1.0000x reference)
.LBB0_1011:
	v_mov_b32_e32 v184, v212
	s_lshl_b32 s11, s42, 8
	v_ashrrev_i32_e32 v136, 2, v184
	s_or_b32 s11, s11, s36
	v_and_b32_e32 v136, -4, v136
	v_add_u32_e32 v136, s11, v136
	v_and_or_b32 v138, v184, 15, s35
	s_lshl_b32 s11, s43, 8
	v_ashrrev_i32_e32 v137, 31, v136
	v_add_u32_e32 v140, s11, v138
	v_lshlrev_b64 v[136:137], 1, v[136:137]
	v_ashrrev_i32_e32 v141, 31, v140
	v_or_b32_e32 v150, 16, v140
	v_lshl_add_u64 v[138:139], s[4:5], 0, v[136:137]
	v_lshlrev_b64 v[168:169], 11, v[140:141]
	v_ashrrev_i32_e32 v151, 31, v150
	v_or_b32_e32 v154, 32, v140
	v_lshl_add_u64 v[142:143], v[138:139], 0, v[168:169]
	v_lshlrev_b64 v[170:171], 11, v[150:151]
	v_ashrrev_i32_e32 v155, 31, v154
	global_load_dwordx2 v[144:145], v[142:143], off
	global_load_dwordx2 v[146:147], v[142:143], off offset:32
	global_load_dwordx2 v[148:149], v[142:143], off offset:256
	global_load_dwordx2 v[152:153], v[142:143], off offset:288
	v_lshl_add_u64 v[142:143], v[138:139], 0, v[170:171]
	v_lshlrev_b64 v[154:155], 11, v[154:155]
	v_or_b32_e32 v174, 48, v140
	global_load_dwordx2 v[150:151], v[142:143], off
	global_load_dwordx2 v[156:157], v[142:143], off offset:32
	global_load_dwordx2 v[158:159], v[142:143], off offset:256
	global_load_dwordx2 v[160:161], v[142:143], off offset:288
	v_lshl_add_u64 v[142:143], v[138:139], 0, v[154:155]
	v_ashrrev_i32_e32 v175, 31, v174
	global_load_dwordx2 v[162:163], v[142:143], off
	global_load_dwordx2 v[164:165], v[142:143], off offset:32
	global_load_dwordx2 v[172:173], v[142:143], off offset:256
	global_load_dwordx2 v[176:177], v[142:143], off offset:288
	v_lshlrev_b64 v[142:143], 11, v[174:175]
	v_lshl_add_u64 v[174:175], v[138:139], 0, v[142:143]
	global_load_dwordx2 v[178:179], v[174:175], off
	global_load_dwordx2 v[180:181], v[174:175], off offset:32
	global_load_dwordx2 v[182:183], v[174:175], off offset:256
	s_nop 0
	global_load_dwordx2 v[174:175], v[174:175], off offset:288
	v_cmp_gt_u32_e32 vcc, 16, v184
	v_add_u32_e32 v141, s35, v184
	v_lshl_add_u64 v[168:169], s[4:5], 0, v[168:169]
	v_lshl_add_u64 v[168:169], v[168:169], 0, v[136:137]
	s_waitcnt vmcnt(0)
	v_lshlrev_b32_e32 v184, 16, v144
	v_and_b32_e32 v185, 0xffff0000, v144
	v_lshlrev_b32_e32 v186, 16, v145
	v_and_b32_e32 v187, 0xffff0000, v145
	v_pk_add_f32 v[126:127], v[126:127], v[184:185]
	v_pk_add_f32 v[128:129], v[128:129], v[186:187]
	v_lshlrev_b32_e32 v188, 16, v146
	v_and_b32_e32 v189, 0xffff0000, v146
	v_lshlrev_b32_e32 v190, 16, v147
	v_and_b32_e32 v191, 0xffff0000, v147
	v_pk_add_f32 v[122:123], v[122:123], v[188:189]
	v_pk_add_f32 v[124:125], v[124:125], v[190:191]
	v_lshlrev_b32_e32 v192, 16, v148
	v_and_b32_e32 v193, 0xffff0000, v148
	v_lshlrev_b32_e32 v194, 16, v149
	v_lshlrev_b32_e32 v144, 16, v174
	v_and_b32_e32 v145, 0xffff0000, v174
	v_cvt_pk_bf16_f32 v174, v126, v127
	v_mul_f32_e32 v127, v127, v127
	v_fmac_f32_e32 v127, v126, v126
	v_mul_f32_e32 v126, v129, v129
	v_fmac_f32_e32 v126, v128, v128
	v_lshlrev_b32_e32 v146, 16, v175
	v_and_b32_e32 v147, 0xffff0000, v175
	v_cvt_pk_bf16_f32 v175, v128, v129
	v_add_f32_e32 v128, v127, v126
	v_cvt_pk_bf16_f32 v126, v122, v123
	v_mul_f32_e32 v123, v123, v123
	v_fmac_f32_e32 v123, v122, v122
	v_mul_f32_e32 v122, v125, v125
	v_fmac_f32_e32 v122, v124, v124
	v_and_b32_e32 v195, 0xffff0000, v149
	v_add_f32_e32 v122, v123, v122
	v_pk_add_f32 v[118:119], v[118:119], v[192:193]
	v_cvt_pk_bf16_f32 v127, v124, v125
	v_add_f32_e32 v124, v128, v122
	v_pk_add_f32 v[120:121], v[120:121], v[194:195]
	v_cvt_pk_bf16_f32 v122, v118, v119
	v_mul_f32_e32 v119, v119, v119
	v_fmac_f32_e32 v119, v118, v118
	v_mul_f32_e32 v118, v121, v121
	v_lshlrev_b32_e32 v196, 16, v152
	v_and_b32_e32 v197, 0xffff0000, v152
	v_fmac_f32_e32 v118, v120, v120
	v_lshlrev_b32_e32 v198, 16, v153
	v_and_b32_e32 v199, 0xffff0000, v153
	v_add_f32_e32 v118, v119, v118
	v_pk_add_f32 v[110:111], v[110:111], v[196:197]
	v_cvt_pk_bf16_f32 v123, v120, v121
	v_add_f32_e32 v120, v124, v118
	v_pk_add_f32 v[112:113], v[112:113], v[198:199]
	v_cvt_pk_bf16_f32 v118, v110, v111
	v_mul_f32_e32 v111, v111, v111
	v_fmac_f32_e32 v111, v110, v110
	v_mul_f32_e32 v110, v113, v113
	v_fmac_f32_e32 v110, v112, v112
	v_lshlrev_b32_e32 v202, 16, v151
	v_and_b32_e32 v203, 0xffff0000, v151
	v_cvt_pk_bf16_f32 v119, v112, v113
	v_add_f32_e32 v110, v111, v110
	v_lshlrev_b32_e32 v200, 16, v150
	v_and_b32_e32 v201, 0xffff0000, v150
	v_lshlrev_b32_e32 v204, 16, v156
	v_and_b32_e32 v205, 0xffff0000, v156
	global_store_dwordx2 v[168:169], v[118:119], off offset:288
	v_add_u32_e32 v128, 0x80, v140
	v_ashrrev_i32_e32 v129, 31, v128
	v_lshlrev_b64 v[128:129], 11, v[128:129]
	v_lshl_add_u64 v[128:129], v[138:139], 0, v[128:129]
	v_mov_b32_e32 v124, 0x8000
	v_mov_b32_e32 v125, 0
	global_load_dwordx2 v[250:251], v[128:129], off
	global_load_dwordx2 v[248:249], v[128:129], off offset:32
	global_load_dwordx2 v[246:247], v[128:129], off offset:256
	global_load_dwordx2 v[244:245], v[128:129], off offset:288
	v_lshl_add_u64 v[128:129], v[128:129], 0, v[124:125]
	global_load_dwordx2 v[242:243], v[128:129], off
	global_load_dwordx2 v[240:241], v[128:129], off offset:32
	global_load_dwordx2 v[238:239], v[128:129], off offset:256
	global_load_dwordx2 v[236:237], v[128:129], off offset:288
	v_lshl_add_u64 v[128:129], v[128:129], 0, v[124:125]
	global_load_dwordx2 v[198:199], v[128:129], off
	global_load_dwordx2 v[196:197], v[128:129], off offset:32
	global_load_dwordx2 v[194:195], v[128:129], off offset:256
	global_load_dwordx2 v[192:193], v[128:129], off offset:288
	v_lshl_add_u64 v[128:129], v[128:129], 0, v[124:125]
	global_load_dwordx2 v[190:191], v[128:129], off
	global_load_dwordx2 v[188:189], v[128:129], off offset:32
	global_load_dwordx2 v[186:187], v[128:129], off offset:256
	global_load_dwordx2 v[184:185], v[128:129], off offset:288
	v_add_f32_e32 v118, v120, v110
	v_pk_add_f32 v[110:111], v[116:117], v[202:203]
	v_lshlrev_b32_e32 v206, 16, v157
	v_and_b32_e32 v207, 0xffff0000, v157
	v_pk_add_f32 v[112:113], v[114:115], v[200:201]
	v_cvt_pk_bf16_f32 v115, v110, v111
	v_mul_f32_e32 v111, v111, v111
	v_pk_add_f32 v[106:107], v[106:107], v[204:205]
	v_fmac_f32_e32 v111, v110, v110
	v_pk_add_f32 v[108:109], v[108:109], v[206:207]
	v_cvt_pk_bf16_f32 v110, v106, v107
	v_mul_f32_e32 v107, v107, v107
	v_cvt_pk_bf16_f32 v114, v112, v113
	v_mul_f32_e32 v113, v113, v113
	v_fmac_f32_e32 v107, v106, v106
	v_mul_f32_e32 v106, v109, v109
	v_lshlrev_b32_e32 v210, 16, v158
	v_and_b32_e32 v211, 0xffff0000, v158
	v_fmac_f32_e32 v113, v112, v112
	v_fmac_f32_e32 v106, v108, v108
	v_lshlrev_b32_e32 v214, 16, v159
	v_and_b32_e32 v215, 0xffff0000, v159
	v_add_f32_e32 v112, v113, v111
	v_add_f32_e32 v106, v107, v106
	v_pk_add_f32 v[102:103], v[102:103], v[210:211]
	v_cvt_pk_bf16_f32 v111, v108, v109
	v_add_f32_e32 v108, v112, v106
	v_pk_add_f32 v[104:105], v[104:105], v[214:215]
	v_cvt_pk_bf16_f32 v106, v102, v103
	v_mul_f32_e32 v103, v103, v103
	v_fmac_f32_e32 v103, v102, v102
	v_mul_f32_e32 v102, v105, v105
	v_lshlrev_b32_e32 v216, 16, v160
	v_and_b32_e32 v217, 0xffff0000, v160
	v_fmac_f32_e32 v102, v104, v104
	v_lshlrev_b32_e32 v224, 16, v161
	v_and_b32_e32 v225, 0xffff0000, v161
	v_add_f32_e32 v102, v103, v102
	v_pk_add_f32 v[94:95], v[94:95], v[216:217]
	v_cvt_pk_bf16_f32 v107, v104, v105
	v_add_f32_e32 v104, v108, v102
	v_pk_add_f32 v[96:97], v[96:97], v[224:225]
	v_cvt_pk_bf16_f32 v102, v94, v95
	v_mul_f32_e32 v95, v95, v95
	v_fmac_f32_e32 v95, v94, v94
	v_mul_f32_e32 v94, v97, v97
	v_lshl_add_u64 v[116:117], s[4:5], 0, v[170:171]
	v_fmac_f32_e32 v94, v96, v96
	v_lshlrev_b32_e32 v228, 16, v163
	v_and_b32_e32 v229, 0xffff0000, v163
	v_lshl_add_u64 v[116:117], v[116:117], 0, v[136:137]
	v_cvt_pk_bf16_f32 v103, v96, v97
	v_add_f32_e32 v94, v95, v94
	v_lshlrev_b32_e32 v226, 16, v162
	v_and_b32_e32 v227, 0xffff0000, v162
	v_lshlrev_b32_e32 v230, 16, v164
	v_and_b32_e32 v231, 0xffff0000, v164
	global_store_dwordx2 v[116:117], v[102:103], off offset:288
	v_add_f32_e32 v102, v104, v94
	v_pk_add_f32 v[94:95], v[100:101], v[228:229]
	v_lshlrev_b32_e32 v232, 16, v165
	v_and_b32_e32 v233, 0xffff0000, v165
	v_pk_add_f32 v[96:97], v[98:99], v[226:227]
	v_cvt_pk_bf16_f32 v99, v94, v95
	v_mul_f32_e32 v95, v95, v95
	v_pk_add_f32 v[90:91], v[90:91], v[230:231]
	v_fmac_f32_e32 v95, v94, v94
	v_pk_add_f32 v[92:93], v[92:93], v[232:233]
	v_cvt_pk_bf16_f32 v94, v90, v91
	v_mul_f32_e32 v91, v91, v91
	v_cvt_pk_bf16_f32 v98, v96, v97
	v_mul_f32_e32 v97, v97, v97
	v_fmac_f32_e32 v91, v90, v90
	v_mul_f32_e32 v90, v93, v93
	v_lshlrev_b32_e32 v234, 16, v172
	v_and_b32_e32 v235, 0xffff0000, v172
	v_fmac_f32_e32 v97, v96, v96
	v_fmac_f32_e32 v90, v92, v92
	v_lshlrev_b32_e32 v172, 16, v173
	v_and_b32_e32 v173, 0xffff0000, v173
	v_add_f32_e32 v96, v97, v95
	v_add_f32_e32 v90, v91, v90
	v_pk_add_f32 v[86:87], v[86:87], v[234:235]
	v_cvt_pk_bf16_f32 v95, v92, v93
	v_add_f32_e32 v92, v96, v90
	v_pk_add_f32 v[88:89], v[88:89], v[172:173]
	v_cvt_pk_bf16_f32 v90, v86, v87
	v_mul_f32_e32 v87, v87, v87
	v_fmac_f32_e32 v87, v86, v86
	v_mul_f32_e32 v86, v89, v89
	v_lshlrev_b32_e32 v162, 16, v176
	v_and_b32_e32 v163, 0xffff0000, v176
	v_fmac_f32_e32 v86, v88, v88
	v_lshlrev_b32_e32 v164, 16, v177
	v_and_b32_e32 v165, 0xffff0000, v177
	v_add_f32_e32 v86, v87, v86
	v_pk_add_f32 v[78:79], v[78:79], v[162:163]
	v_cvt_pk_bf16_f32 v91, v88, v89
	v_add_f32_e32 v88, v92, v86
	v_pk_add_f32 v[80:81], v[80:81], v[164:165]
	v_cvt_pk_bf16_f32 v86, v78, v79
	v_mul_f32_e32 v79, v79, v79
	v_fmac_f32_e32 v79, v78, v78
	v_mul_f32_e32 v78, v81, v81
	v_lshl_add_u64 v[100:101], s[4:5], 0, v[154:155]
	v_fmac_f32_e32 v78, v80, v80
	v_lshlrev_b32_e32 v160, 16, v179
	v_and_b32_e32 v161, 0xffff0000, v179
	v_lshl_add_u64 v[100:101], v[100:101], 0, v[136:137]
	v_cvt_pk_bf16_f32 v87, v80, v81
	v_add_f32_e32 v78, v79, v78
	v_lshlrev_b32_e32 v158, 16, v178
	v_and_b32_e32 v159, 0xffff0000, v178
	v_lshlrev_b32_e32 v152, 16, v180
	v_and_b32_e32 v153, 0xffff0000, v180
	global_store_dwordx2 v[100:101], v[86:87], off offset:288
	v_add_f32_e32 v86, v88, v78
	v_pk_add_f32 v[78:79], v[84:85], v[160:161]
	v_lshlrev_b32_e32 v156, 16, v181
	v_and_b32_e32 v157, 0xffff0000, v181
	v_pk_add_f32 v[80:81], v[82:83], v[158:159]
	v_cvt_pk_bf16_f32 v83, v78, v79
	v_mul_f32_e32 v79, v79, v79
	v_pk_add_f32 v[74:75], v[74:75], v[152:153]
	v_fmac_f32_e32 v79, v78, v78
	v_pk_add_f32 v[76:77], v[76:77], v[156:157]
	v_cvt_pk_bf16_f32 v78, v74, v75
	v_mul_f32_e32 v75, v75, v75
	v_cvt_pk_bf16_f32 v82, v80, v81
	v_mul_f32_e32 v81, v81, v81
	v_fmac_f32_e32 v75, v74, v74
	v_mul_f32_e32 v74, v77, v77
	v_lshlrev_b32_e32 v148, 16, v182
	v_and_b32_e32 v149, 0xffff0000, v182
	v_fmac_f32_e32 v81, v80, v80
	v_fmac_f32_e32 v74, v76, v76
	v_lshlrev_b32_e32 v150, 16, v183
	v_and_b32_e32 v151, 0xffff0000, v183
	v_add_f32_e32 v80, v81, v79
	v_add_f32_e32 v74, v75, v74
	v_pk_add_f32 v[70:71], v[70:71], v[148:149]
	v_cvt_pk_bf16_f32 v79, v76, v77
	v_add_f32_e32 v76, v80, v74
	v_pk_add_f32 v[72:73], v[72:73], v[150:151]
	v_cvt_pk_bf16_f32 v74, v70, v71
	v_mul_f32_e32 v71, v71, v71
	v_fmac_f32_e32 v71, v70, v70
	v_mul_f32_e32 v70, v73, v73
	v_fmac_f32_e32 v70, v72, v72
	v_add_f32_e32 v70, v71, v70
	v_pk_add_f32 v[66:67], v[66:67], v[144:145]
	v_cvt_pk_bf16_f32 v75, v72, v73
	v_add_f32_e32 v72, v76, v70
	v_pk_add_f32 v[68:69], v[68:69], v[146:147]
	v_cvt_pk_bf16_f32 v70, v66, v67
	v_mul_f32_e32 v67, v67, v67
	v_fmac_f32_e32 v67, v66, v66
	v_mul_f32_e32 v66, v69, v69
	v_fmac_f32_e32 v66, v68, v68
	v_lshl_add_u64 v[84:85], s[4:5], 0, v[142:143]
	v_add_f32_e32 v66, v67, v66
	v_lshl_add_u64 v[84:85], v[84:85], 0, v[136:137]
	v_cvt_pk_bf16_f32 v71, v68, v69
	v_add_f32_e32 v66, v72, v66
	global_store_dwordx2 v[84:85], v[70:71], off offset:288
	v_mov_b32_e32 v67, v118
	v_mov_b32_e32 v68, v102
	v_mov_b32_e32 v69, v86
	v_mov_b32_e32 v70, v66
	v_permlane16_swap_b32_e32 v118, v67
	v_permlane16_swap_b32_e32 v102, v68
	v_permlane16_swap_b32_e32 v86, v69
	v_permlane16_swap_b32_e32 v66, v70
	v_add_f32_e32 v67, v118, v67
	v_add_f32_e32 v68, v102, v68
	v_add_f32_e32 v69, v86, v69
	v_add_f32_e32 v71, v66, v70
	global_store_dwordx2 v[84:85], v[74:75], off offset:256
	v_mov_b32_e32 v70, v67
	v_mov_b32_e32 v72, v68
	v_mov_b32_e32 v73, v69
	v_mov_b32_e32 v74, v71
	v_permlane32_swap_b32_e32 v67, v70
	v_permlane32_swap_b32_e32 v68, v72
	v_permlane32_swap_b32_e32 v69, v73
	v_permlane32_swap_b32_e32 v71, v74
	v_add_u32_e32 v66, s11, v141
	global_store_dwordx2 v[168:169], v[174:175], off
	global_store_dwordx2 v[168:169], v[126:127], off offset:32
	global_store_dwordx2 v[168:169], v[122:123], off offset:256
	global_store_dwordx2 v[116:117], v[114:115], off
	global_store_dwordx2 v[116:117], v[110:111], off offset:32
	global_store_dwordx2 v[116:117], v[106:107], off offset:256
	global_store_dwordx2 v[100:101], v[98:99], off
	global_store_dwordx2 v[100:101], v[94:95], off offset:32
	global_store_dwordx2 v[100:101], v[90:91], off offset:256
	global_store_dwordx2 v[84:85], v[82:83], off
	global_store_dwordx2 v[84:85], v[78:79], off offset:32
	s_and_saveexec_b64 s[18:19], vcc
	s_cbranch_execz .LBB0_1013
	s_lshl_b32 s20, s42, 2
	s_ashr_i32 s21, s20, 31
	s_lshl_b64 s[20:21], s[20:21], 2
	s_add_u32 s20, s39, s20
	v_add_f32_e32 v70, v67, v70
	v_ashrrev_i32_e32 v67, 31, v66
	s_addc_u32 s21, s40, s21
	v_add_f32_e32 v73, v69, v73
	v_add_f32_e32 v72, v68, v72
	v_lshlrev_b64 v[68:69], 6, v[66:67]
	v_lshl_add_u64 v[68:69], s[20:21], 0, v[68:69]
	global_store_dword v[68:69], v70, off
	v_or_b32_e32 v68, 16, v66
	v_ashrrev_i32_e32 v69, 31, v68
	v_lshlrev_b64 v[68:69], 6, v[68:69]
	v_lshl_add_u64 v[68:69], s[20:21], 0, v[68:69]
	global_store_dword v[68:69], v72, off
	v_or_b32_e32 v68, 32, v66
	v_ashrrev_i32_e32 v69, 31, v68
	v_lshlrev_b64 v[68:69], 6, v[68:69]
	v_lshl_add_u64 v[68:69], s[20:21], 0, v[68:69]
	global_store_dword v[68:69], v73, off
	v_or_b32_e32 v68, 48, v66
	v_ashrrev_i32_e32 v69, 31, v68
	v_lshlrev_b64 v[68:69], 6, v[68:69]
	v_add_f32_e32 v71, v71, v74
	v_lshl_add_u64 v[68:69], s[20:21], 0, v[68:69]
	global_store_dword v[68:69], v71, off
.LBB0_1013:
	s_or_b64 exec, exec, s[18:19]
	v_add_u32_e32 v68, 0x80, v140
	v_ashrrev_i32_e32 v69, 31, v68
	v_add_u32_e32 v76, 0x90, v140
	v_lshlrev_b64 v[92:93], 11, v[68:69]
	v_ashrrev_i32_e32 v77, 31, v76
	v_add_u32_e32 v80, 0xa0, v140
	v_lshl_add_u64 v[68:69], v[138:139], 0, v[92:93]
	v_lshlrev_b64 v[94:95], 11, v[76:77]
	v_ashrrev_i32_e32 v81, 31, v80
	v_lshl_add_u64 v[68:69], v[138:139], 0, v[94:95]
	v_lshlrev_b64 v[80:81], 11, v[80:81]
	v_add_u32_e32 v98, 0xb0, v140
	v_lshl_add_u64 v[68:69], v[138:139], 0, v[80:81]
	v_ashrrev_i32_e32 v99, 31, v98
	v_lshlrev_b64 v[68:69], 11, v[98:99]
	v_lshl_add_u64 v[98:99], v[138:139], 0, v[68:69]
	v_lshl_add_u64 v[92:93], s[4:5], 0, v[92:93]
	v_lshl_add_u64 v[92:93], v[92:93], 0, v[136:137]
	s_waitcnt vmcnt(15)
	v_lshlrev_b32_e32 v108, 16, v250
	v_and_b32_e32 v109, 0xffff0000, v250
	v_lshlrev_b32_e32 v110, 16, v251
	v_and_b32_e32 v111, 0xffff0000, v251
	v_pk_add_f32 v[62:63], v[62:63], v[108:109]
	v_pk_add_f32 v[64:65], v[64:65], v[110:111]
	v_lshlrev_b32_e32 v112, 16, v248
	v_and_b32_e32 v113, 0xffff0000, v248
	v_lshlrev_b32_e32 v114, 16, v249
	v_and_b32_e32 v115, 0xffff0000, v249
	v_pk_add_f32 v[58:59], v[58:59], v[112:113]
	v_pk_add_f32 v[60:61], v[60:61], v[114:115]
	v_lshlrev_b32_e32 v116, 16, v246
	v_and_b32_e32 v117, 0xffff0000, v246
	v_lshlrev_b32_e32 v118, 16, v247
	v_lshlrev_b32_e32 v70, 16, v184
	v_and_b32_e32 v71, 0xffff0000, v184
	v_cvt_pk_bf16_f32 v98, v62, v63
	v_mul_f32_e32 v63, v63, v63
	v_fmac_f32_e32 v63, v62, v62
	v_mul_f32_e32 v62, v65, v65
	v_fmac_f32_e32 v62, v64, v64
	v_lshlrev_b32_e32 v72, 16, v185
	v_and_b32_e32 v73, 0xffff0000, v185
	v_cvt_pk_bf16_f32 v99, v64, v65
	v_add_f32_e32 v64, v63, v62
	v_cvt_pk_bf16_f32 v62, v58, v59
	v_mul_f32_e32 v59, v59, v59
	v_fmac_f32_e32 v59, v58, v58
	v_mul_f32_e32 v58, v61, v61
	v_fmac_f32_e32 v58, v60, v60
	v_and_b32_e32 v119, 0xffff0000, v247
	v_add_f32_e32 v58, v59, v58
	v_pk_add_f32 v[54:55], v[54:55], v[116:117]
	v_cvt_pk_bf16_f32 v63, v60, v61
	v_add_f32_e32 v60, v64, v58
	v_pk_add_f32 v[56:57], v[56:57], v[118:119]
	v_cvt_pk_bf16_f32 v58, v54, v55
	v_mul_f32_e32 v55, v55, v55
	v_fmac_f32_e32 v55, v54, v54
	v_mul_f32_e32 v54, v57, v57
	v_lshlrev_b32_e32 v120, 16, v244
	v_and_b32_e32 v121, 0xffff0000, v244
	v_fmac_f32_e32 v54, v56, v56
	v_lshlrev_b32_e32 v122, 16, v245
	v_and_b32_e32 v123, 0xffff0000, v245
	v_add_f32_e32 v54, v55, v54
	v_pk_add_f32 v[46:47], v[46:47], v[120:121]
	v_cvt_pk_bf16_f32 v59, v56, v57
	v_add_f32_e32 v56, v60, v54
	v_pk_add_f32 v[48:49], v[48:49], v[122:123]
	v_cvt_pk_bf16_f32 v54, v46, v47
	v_mul_f32_e32 v47, v47, v47
	v_fmac_f32_e32 v47, v46, v46
	v_mul_f32_e32 v46, v49, v49
	v_fmac_f32_e32 v46, v48, v48
	v_lshlrev_b32_e32 v126, 16, v243
	v_and_b32_e32 v127, 0xffff0000, v243
	v_cvt_pk_bf16_f32 v55, v48, v49
	v_add_f32_e32 v46, v47, v46
	v_lshlrev_b32_e32 v124, 16, v242
	v_and_b32_e32 v125, 0xffff0000, v242
	v_lshlrev_b32_e32 v128, 16, v240
	v_and_b32_e32 v129, 0xffff0000, v240
	global_store_dwordx2 v[92:93], v[54:55], off offset:288
	v_add_f32_e32 v54, v56, v46
	v_pk_add_f32 v[46:47], v[52:53], v[126:127]
	v_lshlrev_b32_e32 v138, 16, v241
	v_and_b32_e32 v139, 0xffff0000, v241
	v_pk_add_f32 v[48:49], v[50:51], v[124:125]
	v_cvt_pk_bf16_f32 v51, v46, v47
	v_mul_f32_e32 v47, v47, v47
	v_pk_add_f32 v[42:43], v[42:43], v[128:129]
	v_fmac_f32_e32 v47, v46, v46
	v_pk_add_f32 v[44:45], v[44:45], v[138:139]
	v_cvt_pk_bf16_f32 v46, v42, v43
	v_mul_f32_e32 v43, v43, v43
	v_cvt_pk_bf16_f32 v50, v48, v49
	v_mul_f32_e32 v49, v49, v49
	v_fmac_f32_e32 v43, v42, v42
	v_mul_f32_e32 v42, v45, v45
	v_lshlrev_b32_e32 v140, 16, v238
	v_and_b32_e32 v141, 0xffff0000, v238
	v_fmac_f32_e32 v49, v48, v48
	v_fmac_f32_e32 v42, v44, v44
	v_lshlrev_b32_e32 v142, 16, v239
	v_and_b32_e32 v143, 0xffff0000, v239
	v_add_f32_e32 v48, v49, v47
	v_add_f32_e32 v42, v43, v42
	v_pk_add_f32 v[38:39], v[38:39], v[140:141]
	v_cvt_pk_bf16_f32 v47, v44, v45
	v_add_f32_e32 v44, v48, v42
	v_pk_add_f32 v[40:41], v[40:41], v[142:143]
	v_cvt_pk_bf16_f32 v42, v38, v39
	v_mul_f32_e32 v39, v39, v39
	v_fmac_f32_e32 v39, v38, v38
	v_mul_f32_e32 v38, v41, v41
	v_lshlrev_b32_e32 v144, 16, v236
	v_and_b32_e32 v145, 0xffff0000, v236
	v_fmac_f32_e32 v38, v40, v40
	v_lshlrev_b32_e32 v146, 16, v237
	v_and_b32_e32 v147, 0xffff0000, v237
	v_add_f32_e32 v38, v39, v38
	v_pk_add_f32 v[30:31], v[30:31], v[144:145]
	v_cvt_pk_bf16_f32 v43, v40, v41
	v_add_f32_e32 v40, v44, v38
	v_pk_add_f32 v[32:33], v[32:33], v[146:147]
	v_cvt_pk_bf16_f32 v38, v30, v31
	v_mul_f32_e32 v31, v31, v31
	v_fmac_f32_e32 v31, v30, v30
	v_mul_f32_e32 v30, v33, v33
	v_lshl_add_u64 v[52:53], s[4:5], 0, v[94:95]
	v_fmac_f32_e32 v30, v32, v32
	v_lshlrev_b32_e32 v150, 16, v199
	v_and_b32_e32 v151, 0xffff0000, v199
	v_lshl_add_u64 v[52:53], v[52:53], 0, v[136:137]
	v_cvt_pk_bf16_f32 v39, v32, v33
	v_add_f32_e32 v30, v31, v30
	v_lshlrev_b32_e32 v148, 16, v198
	v_and_b32_e32 v149, 0xffff0000, v198
	v_lshlrev_b32_e32 v152, 16, v196
	v_and_b32_e32 v153, 0xffff0000, v196
	global_store_dwordx2 v[52:53], v[38:39], off offset:288
	v_add_f32_e32 v38, v40, v30
	v_pk_add_f32 v[30:31], v[36:37], v[150:151]
	v_lshlrev_b32_e32 v154, 16, v197
	v_and_b32_e32 v155, 0xffff0000, v197
	v_pk_add_f32 v[32:33], v[34:35], v[148:149]
	v_cvt_pk_bf16_f32 v35, v30, v31
	v_mul_f32_e32 v31, v31, v31
	v_pk_add_f32 v[26:27], v[26:27], v[152:153]
	v_fmac_f32_e32 v31, v30, v30
	v_pk_add_f32 v[28:29], v[28:29], v[154:155]
	v_cvt_pk_bf16_f32 v30, v26, v27
	v_mul_f32_e32 v27, v27, v27
	v_cvt_pk_bf16_f32 v34, v32, v33
	v_mul_f32_e32 v33, v33, v33
	v_fmac_f32_e32 v27, v26, v26
	v_mul_f32_e32 v26, v29, v29
	v_lshlrev_b32_e32 v156, 16, v194
	v_and_b32_e32 v157, 0xffff0000, v194
	v_fmac_f32_e32 v33, v32, v32
	v_fmac_f32_e32 v26, v28, v28
	v_lshlrev_b32_e32 v96, 16, v195
	v_and_b32_e32 v97, 0xffff0000, v195
	v_add_f32_e32 v32, v33, v31
	v_add_f32_e32 v26, v27, v26
	v_pk_add_f32 v[22:23], v[22:23], v[156:157]
	v_cvt_pk_bf16_f32 v31, v28, v29
	v_add_f32_e32 v28, v32, v26
	v_pk_add_f32 v[24:25], v[24:25], v[96:97]
	v_cvt_pk_bf16_f32 v26, v22, v23
	v_mul_f32_e32 v23, v23, v23
	v_fmac_f32_e32 v23, v22, v22
	v_mul_f32_e32 v22, v25, v25
	v_lshlrev_b32_e32 v88, 16, v192
	v_and_b32_e32 v89, 0xffff0000, v192
	v_fmac_f32_e32 v22, v24, v24
	v_lshlrev_b32_e32 v90, 16, v193
	v_and_b32_e32 v91, 0xffff0000, v193
	v_add_f32_e32 v22, v23, v22
	v_pk_add_f32 v[14:15], v[14:15], v[88:89]
	v_cvt_pk_bf16_f32 v27, v24, v25
	v_add_f32_e32 v24, v28, v22
	v_pk_add_f32 v[16:17], v[16:17], v[90:91]
	v_cvt_pk_bf16_f32 v22, v14, v15
	v_mul_f32_e32 v15, v15, v15
	v_fmac_f32_e32 v15, v14, v14
	v_mul_f32_e32 v14, v17, v17
	v_lshl_add_u64 v[36:37], s[4:5], 0, v[80:81]
	v_fmac_f32_e32 v14, v16, v16
	v_lshlrev_b32_e32 v86, 16, v191
	v_and_b32_e32 v87, 0xffff0000, v191
	v_lshl_add_u64 v[36:37], v[36:37], 0, v[136:137]
	v_cvt_pk_bf16_f32 v23, v16, v17
	v_add_f32_e32 v14, v15, v14
	v_lshlrev_b32_e32 v84, 16, v190
	v_and_b32_e32 v85, 0xffff0000, v190
	v_lshlrev_b32_e32 v78, 16, v188
	v_and_b32_e32 v79, 0xffff0000, v188
	global_store_dwordx2 v[36:37], v[22:23], off offset:288
	v_add_f32_e32 v22, v24, v14
	v_pk_add_f32 v[14:15], v[20:21], v[86:87]
	v_lshlrev_b32_e32 v82, 16, v189
	v_and_b32_e32 v83, 0xffff0000, v189
	v_pk_add_f32 v[16:17], v[18:19], v[84:85]
	v_cvt_pk_bf16_f32 v19, v14, v15
	v_mul_f32_e32 v15, v15, v15
	v_pk_add_f32 v[10:11], v[10:11], v[78:79]
	v_fmac_f32_e32 v15, v14, v14
	v_pk_add_f32 v[12:13], v[12:13], v[82:83]
	v_cvt_pk_bf16_f32 v14, v10, v11
	v_mul_f32_e32 v11, v11, v11
	v_cvt_pk_bf16_f32 v18, v16, v17
	v_mul_f32_e32 v17, v17, v17
	v_fmac_f32_e32 v11, v10, v10
	v_mul_f32_e32 v10, v13, v13
	v_lshlrev_b32_e32 v74, 16, v186
	v_and_b32_e32 v75, 0xffff0000, v186
	v_fmac_f32_e32 v17, v16, v16
	v_fmac_f32_e32 v10, v12, v12
	v_lshlrev_b32_e32 v76, 16, v187
	v_and_b32_e32 v77, 0xffff0000, v187
	v_add_f32_e32 v16, v17, v15
	v_add_f32_e32 v10, v11, v10
	v_pk_add_f32 v[6:7], v[6:7], v[74:75]
	v_cvt_pk_bf16_f32 v15, v12, v13
	v_add_f32_e32 v12, v16, v10
	v_pk_add_f32 v[8:9], v[8:9], v[76:77]
	v_cvt_pk_bf16_f32 v10, v6, v7
	v_mul_f32_e32 v7, v7, v7
	v_fmac_f32_e32 v7, v6, v6
	v_mul_f32_e32 v6, v9, v9
	v_fmac_f32_e32 v6, v8, v8
	v_add_f32_e32 v6, v7, v6
	v_pk_add_f32 v[2:3], v[2:3], v[70:71]
	v_cvt_pk_bf16_f32 v11, v8, v9
	v_add_f32_e32 v8, v12, v6
	v_pk_add_f32 v[4:5], v[4:5], v[72:73]
	v_cvt_pk_bf16_f32 v6, v2, v3
	v_mul_f32_e32 v3, v3, v3
	v_fmac_f32_e32 v3, v2, v2
	v_mul_f32_e32 v2, v5, v5
	v_fmac_f32_e32 v2, v4, v4
	v_lshl_add_u64 v[20:21], s[4:5], 0, v[68:69]
	v_add_f32_e32 v2, v3, v2
	v_lshl_add_u64 v[20:21], v[20:21], 0, v[136:137]
	v_cvt_pk_bf16_f32 v7, v4, v5
	v_add_f32_e32 v5, v8, v2
	global_store_dwordx2 v[20:21], v[6:7], off offset:288
	v_mov_b32_e32 v2, v54
	v_mov_b32_e32 v3, v38
	v_mov_b32_e32 v4, v22
	v_mov_b32_e32 v6, v5
	v_permlane16_swap_b32_e32 v54, v2
	v_permlane16_swap_b32_e32 v38, v3
	v_permlane16_swap_b32_e32 v22, v4
	v_permlane16_swap_b32_e32 v5, v6
	v_add_f32_e32 v2, v54, v2
	v_add_f32_e32 v3, v38, v3
	v_add_f32_e32 v4, v22, v4
	v_add_f32_e32 v6, v5, v6
	v_mov_b32_e32 v5, v2
	v_mov_b32_e32 v7, v3
	v_mov_b32_e32 v8, v4
	v_mov_b32_e32 v9, v6
	v_permlane32_swap_b32_e32 v2, v5
	v_permlane32_swap_b32_e32 v3, v7
	v_permlane32_swap_b32_e32 v4, v8
	v_permlane32_swap_b32_e32 v6, v9
	global_store_dwordx2 v[92:93], v[98:99], off
	global_store_dwordx2 v[92:93], v[62:63], off offset:32
	global_store_dwordx2 v[92:93], v[58:59], off offset:256
	global_store_dwordx2 v[52:53], v[50:51], off
	global_store_dwordx2 v[52:53], v[46:47], off offset:32
	global_store_dwordx2 v[52:53], v[42:43], off offset:256
	global_store_dwordx2 v[36:37], v[34:35], off
	global_store_dwordx2 v[36:37], v[30:31], off offset:32
	global_store_dwordx2 v[36:37], v[26:27], off offset:256
	global_store_dwordx2 v[20:21], v[18:19], off
	global_store_dwordx2 v[20:21], v[14:15], off offset:32
	global_store_dwordx2 v[20:21], v[10:11], off offset:256
	s_and_saveexec_b64 s[18:19], vcc
	s_cbranch_execz .LBB0_1015
	s_lshl_b32 s20, s42, 2
	s_ashr_i32 s21, s20, 31
	s_lshl_b64 s[20:21], s[20:21], 2
	v_add_u32_e32 v10, 0x80, v66
	s_add_u32 s20, s39, s20
	v_ashrrev_i32_e32 v11, 31, v10
	s_addc_u32 s21, s40, s21
	v_add_f32_e32 v7, v3, v7
	v_add_f32_e32 v5, v2, v5
	v_lshlrev_b64 v[2:3], 6, v[10:11]
	v_lshl_add_u64 v[2:3], s[20:21], 0, v[2:3]
	global_store_dword v[2:3], v5, off
	v_add_u32_e32 v2, 0x90, v66
	v_ashrrev_i32_e32 v3, 31, v2
	v_lshlrev_b64 v[2:3], 6, v[2:3]
	v_lshl_add_u64 v[2:3], s[20:21], 0, v[2:3]
	global_store_dword v[2:3], v7, off
	v_add_u32_e32 v2, 0xa0, v66
	v_ashrrev_i32_e32 v3, 31, v2
	v_lshlrev_b64 v[2:3], 6, v[2:3]
	v_add_f32_e32 v4, v4, v8
	v_lshl_add_u64 v[2:3], s[20:21], 0, v[2:3]
	global_store_dword v[2:3], v4, off
	v_add_u32_e32 v2, 0xb0, v66
	v_ashrrev_i32_e32 v3, 31, v2
	v_lshlrev_b64 v[2:3], 6, v[2:3]
	v_add_f32_e32 v6, v6, v9
	v_lshl_add_u64 v[2:3], s[20:21], 0, v[2:3]
	global_store_dword v[2:3], v6, off

.LBB0_1345:
	v_mov_b32_e32 v184, v212
	s_lshl_b32 s14, s40, 8
	v_ashrrev_i32_e32 v136, 2, v184
	s_or_b32 s14, s14, s36
	v_and_b32_e32 v136, -4, v136
	v_add_u32_e32 v136, s14, v136
	v_and_or_b32 v138, v184, 15, s31
	s_lshl_b32 s14, s43, 8
	v_ashrrev_i32_e32 v137, 31, v136
	v_add_u32_e32 v140, s14, v138
	v_lshlrev_b64 v[136:137], 1, v[136:137]
	v_ashrrev_i32_e32 v141, 31, v140
	v_or_b32_e32 v150, 16, v140
	v_lshl_add_u64 v[138:139], s[2:3], 0, v[136:137]
	v_lshlrev_b64 v[168:169], 11, v[140:141]
	v_ashrrev_i32_e32 v151, 31, v150
	v_or_b32_e32 v154, 32, v140
	v_lshl_add_u64 v[142:143], v[138:139], 0, v[168:169]
	v_lshlrev_b64 v[170:171], 11, v[150:151]
	v_ashrrev_i32_e32 v155, 31, v154
	global_load_dwordx2 v[144:145], v[142:143], off
	global_load_dwordx2 v[146:147], v[142:143], off offset:32
	global_load_dwordx2 v[148:149], v[142:143], off offset:256
	global_load_dwordx2 v[152:153], v[142:143], off offset:288
	v_lshl_add_u64 v[142:143], v[138:139], 0, v[170:171]
	v_lshlrev_b64 v[154:155], 11, v[154:155]
	v_or_b32_e32 v174, 48, v140
	global_load_dwordx2 v[150:151], v[142:143], off
	global_load_dwordx2 v[156:157], v[142:143], off offset:32
	global_load_dwordx2 v[158:159], v[142:143], off offset:256
	global_load_dwordx2 v[160:161], v[142:143], off offset:288
	v_lshl_add_u64 v[142:143], v[138:139], 0, v[154:155]
	v_ashrrev_i32_e32 v175, 31, v174
	global_load_dwordx2 v[162:163], v[142:143], off
	global_load_dwordx2 v[164:165], v[142:143], off offset:32
	global_load_dwordx2 v[172:173], v[142:143], off offset:256
	global_load_dwordx2 v[176:177], v[142:143], off offset:288
	v_lshlrev_b64 v[142:143], 11, v[174:175]
	v_lshl_add_u64 v[174:175], v[138:139], 0, v[142:143]
	global_load_dwordx2 v[178:179], v[174:175], off
	global_load_dwordx2 v[180:181], v[174:175], off offset:32
	global_load_dwordx2 v[182:183], v[174:175], off offset:256
	s_nop 0
	global_load_dwordx2 v[174:175], v[174:175], off offset:288
	v_cmp_gt_u32_e32 vcc, 16, v184
	v_add_u32_e32 v141, s31, v184
	v_lshl_add_u64 v[168:169], s[2:3], 0, v[168:169]
	v_lshl_add_u64 v[168:169], v[168:169], 0, v[136:137]
	s_waitcnt vmcnt(0)
	v_lshlrev_b32_e32 v184, 16, v144
	v_and_b32_e32 v185, 0xffff0000, v144
	v_lshlrev_b32_e32 v186, 16, v145
	v_and_b32_e32 v187, 0xffff0000, v145
	v_pk_add_f32 v[126:127], v[126:127], v[184:185]
	v_pk_add_f32 v[128:129], v[128:129], v[186:187]
	v_lshlrev_b32_e32 v188, 16, v146
	v_and_b32_e32 v189, 0xffff0000, v146
	v_lshlrev_b32_e32 v190, 16, v147
	v_and_b32_e32 v191, 0xffff0000, v147
	v_pk_add_f32 v[122:123], v[122:123], v[188:189]
	v_pk_add_f32 v[124:125], v[124:125], v[190:191]
	v_lshlrev_b32_e32 v192, 16, v148
	v_and_b32_e32 v193, 0xffff0000, v148
	v_lshlrev_b32_e32 v194, 16, v149
	v_lshlrev_b32_e32 v144, 16, v174
	v_and_b32_e32 v145, 0xffff0000, v174
	v_cvt_pk_bf16_f32 v174, v126, v127
	v_mul_f32_e32 v127, v127, v127
	v_fmac_f32_e32 v127, v126, v126
	v_mul_f32_e32 v126, v129, v129
	v_fmac_f32_e32 v126, v128, v128
	v_lshlrev_b32_e32 v146, 16, v175
	v_and_b32_e32 v147, 0xffff0000, v175
	v_cvt_pk_bf16_f32 v175, v128, v129
	v_add_f32_e32 v128, v127, v126
	v_cvt_pk_bf16_f32 v126, v122, v123
	v_mul_f32_e32 v123, v123, v123
	v_fmac_f32_e32 v123, v122, v122
	v_mul_f32_e32 v122, v125, v125
	v_fmac_f32_e32 v122, v124, v124
	v_and_b32_e32 v195, 0xffff0000, v149
	v_add_f32_e32 v122, v123, v122
	v_pk_add_f32 v[118:119], v[118:119], v[192:193]
	v_cvt_pk_bf16_f32 v127, v124, v125
	v_add_f32_e32 v124, v128, v122
	v_pk_add_f32 v[120:121], v[120:121], v[194:195]
	v_cvt_pk_bf16_f32 v122, v118, v119
	v_mul_f32_e32 v119, v119, v119
	v_fmac_f32_e32 v119, v118, v118
	v_mul_f32_e32 v118, v121, v121
	v_lshlrev_b32_e32 v196, 16, v152
	v_and_b32_e32 v197, 0xffff0000, v152
	v_fmac_f32_e32 v118, v120, v120
	v_lshlrev_b32_e32 v198, 16, v153
	v_and_b32_e32 v199, 0xffff0000, v153
	v_add_f32_e32 v118, v119, v118
	v_pk_add_f32 v[110:111], v[110:111], v[196:197]
	v_cvt_pk_bf16_f32 v123, v120, v121
	v_add_f32_e32 v120, v124, v118
	v_pk_add_f32 v[112:113], v[112:113], v[198:199]
	v_cvt_pk_bf16_f32 v118, v110, v111
	v_mul_f32_e32 v111, v111, v111
	v_fmac_f32_e32 v111, v110, v110
	v_mul_f32_e32 v110, v113, v113
	v_fmac_f32_e32 v110, v112, v112
	v_lshlrev_b32_e32 v202, 16, v151
	v_and_b32_e32 v203, 0xffff0000, v151
	v_cvt_pk_bf16_f32 v119, v112, v113
	v_add_f32_e32 v110, v111, v110
	v_lshlrev_b32_e32 v200, 16, v150
	v_and_b32_e32 v201, 0xffff0000, v150
	v_lshlrev_b32_e32 v204, 16, v156
	v_and_b32_e32 v205, 0xffff0000, v156
	global_store_dwordx2 v[168:169], v[118:119], off offset:288
	v_add_u32_e32 v128, 0x80, v140
	v_ashrrev_i32_e32 v129, 31, v128
	v_lshlrev_b64 v[128:129], 11, v[128:129]
	v_lshl_add_u64 v[128:129], v[138:139], 0, v[128:129]
	v_mov_b32_e32 v124, 0x8000
	v_mov_b32_e32 v125, 0
	global_load_dwordx2 v[250:251], v[128:129], off
	global_load_dwordx2 v[248:249], v[128:129], off offset:32
	global_load_dwordx2 v[246:247], v[128:129], off offset:256
	global_load_dwordx2 v[244:245], v[128:129], off offset:288
	v_lshl_add_u64 v[128:129], v[128:129], 0, v[124:125]
	global_load_dwordx2 v[242:243], v[128:129], off
	global_load_dwordx2 v[240:241], v[128:129], off offset:32
	global_load_dwordx2 v[238:239], v[128:129], off offset:256
	global_load_dwordx2 v[236:237], v[128:129], off offset:288
	v_lshl_add_u64 v[128:129], v[128:129], 0, v[124:125]
	global_load_dwordx2 v[198:199], v[128:129], off
	global_load_dwordx2 v[196:197], v[128:129], off offset:32
	global_load_dwordx2 v[194:195], v[128:129], off offset:256
	global_load_dwordx2 v[192:193], v[128:129], off offset:288
	v_lshl_add_u64 v[128:129], v[128:129], 0, v[124:125]
	global_load_dwordx2 v[190:191], v[128:129], off
	global_load_dwordx2 v[188:189], v[128:129], off offset:32
	global_load_dwordx2 v[186:187], v[128:129], off offset:256
	global_load_dwordx2 v[184:185], v[128:129], off offset:288
	v_add_f32_e32 v118, v120, v110
	v_pk_add_f32 v[110:111], v[116:117], v[202:203]
	v_lshlrev_b32_e32 v206, 16, v157
	v_and_b32_e32 v207, 0xffff0000, v157
	v_pk_add_f32 v[112:113], v[114:115], v[200:201]
	v_cvt_pk_bf16_f32 v115, v110, v111
	v_mul_f32_e32 v111, v111, v111
	v_pk_add_f32 v[106:107], v[106:107], v[204:205]
	v_fmac_f32_e32 v111, v110, v110
	v_pk_add_f32 v[108:109], v[108:109], v[206:207]
	v_cvt_pk_bf16_f32 v110, v106, v107
	v_mul_f32_e32 v107, v107, v107
	v_cvt_pk_bf16_f32 v114, v112, v113
	v_mul_f32_e32 v113, v113, v113
	v_fmac_f32_e32 v107, v106, v106
	v_mul_f32_e32 v106, v109, v109
	v_lshlrev_b32_e32 v210, 16, v158
	v_and_b32_e32 v211, 0xffff0000, v158
	v_fmac_f32_e32 v113, v112, v112
	v_fmac_f32_e32 v106, v108, v108
	v_lshlrev_b32_e32 v214, 16, v159
	v_and_b32_e32 v215, 0xffff0000, v159
	v_add_f32_e32 v112, v113, v111
	v_add_f32_e32 v106, v107, v106
	v_pk_add_f32 v[102:103], v[102:103], v[210:211]
	v_cvt_pk_bf16_f32 v111, v108, v109
	v_add_f32_e32 v108, v112, v106
	v_pk_add_f32 v[104:105], v[104:105], v[214:215]
	v_cvt_pk_bf16_f32 v106, v102, v103
	v_mul_f32_e32 v103, v103, v103
	v_fmac_f32_e32 v103, v102, v102
	v_mul_f32_e32 v102, v105, v105
	v_lshlrev_b32_e32 v216, 16, v160
	v_and_b32_e32 v217, 0xffff0000, v160
	v_fmac_f32_e32 v102, v104, v104
	v_lshlrev_b32_e32 v224, 16, v161
	v_and_b32_e32 v225, 0xffff0000, v161
	v_add_f32_e32 v102, v103, v102
	v_pk_add_f32 v[94:95], v[94:95], v[216:217]
	v_cvt_pk_bf16_f32 v107, v104, v105
	v_add_f32_e32 v104, v108, v102
	v_pk_add_f32 v[96:97], v[96:97], v[224:225]
	v_cvt_pk_bf16_f32 v102, v94, v95
	v_mul_f32_e32 v95, v95, v95
	v_fmac_f32_e32 v95, v94, v94
	v_mul_f32_e32 v94, v97, v97
	v_lshl_add_u64 v[116:117], s[2:3], 0, v[170:171]
	v_fmac_f32_e32 v94, v96, v96
	v_lshlrev_b32_e32 v228, 16, v163
	v_and_b32_e32 v229, 0xffff0000, v163
	v_lshl_add_u64 v[116:117], v[116:117], 0, v[136:137]
	v_cvt_pk_bf16_f32 v103, v96, v97
	v_add_f32_e32 v94, v95, v94
	v_lshlrev_b32_e32 v226, 16, v162
	v_and_b32_e32 v227, 0xffff0000, v162
	v_lshlrev_b32_e32 v230, 16, v164
	v_and_b32_e32 v231, 0xffff0000, v164
	global_store_dwordx2 v[116:117], v[102:103], off offset:288
	v_add_f32_e32 v102, v104, v94
	v_pk_add_f32 v[94:95], v[100:101], v[228:229]
	v_lshlrev_b32_e32 v232, 16, v165
	v_and_b32_e32 v233, 0xffff0000, v165
	v_pk_add_f32 v[96:97], v[98:99], v[226:227]
	v_cvt_pk_bf16_f32 v99, v94, v95
	v_mul_f32_e32 v95, v95, v95
	v_pk_add_f32 v[90:91], v[90:91], v[230:231]
	v_fmac_f32_e32 v95, v94, v94
	v_pk_add_f32 v[92:93], v[92:93], v[232:233]
	v_cvt_pk_bf16_f32 v94, v90, v91
	v_mul_f32_e32 v91, v91, v91
	v_cvt_pk_bf16_f32 v98, v96, v97
	v_mul_f32_e32 v97, v97, v97
	v_fmac_f32_e32 v91, v90, v90
	v_mul_f32_e32 v90, v93, v93
	v_lshlrev_b32_e32 v234, 16, v172
	v_and_b32_e32 v235, 0xffff0000, v172
	v_fmac_f32_e32 v97, v96, v96
	v_fmac_f32_e32 v90, v92, v92
	v_lshlrev_b32_e32 v172, 16, v173
	v_and_b32_e32 v173, 0xffff0000, v173
	v_add_f32_e32 v96, v97, v95
	v_add_f32_e32 v90, v91, v90
	v_pk_add_f32 v[86:87], v[86:87], v[234:235]
	v_cvt_pk_bf16_f32 v95, v92, v93
	v_add_f32_e32 v92, v96, v90
	v_pk_add_f32 v[88:89], v[88:89], v[172:173]
	v_cvt_pk_bf16_f32 v90, v86, v87
	v_mul_f32_e32 v87, v87, v87
	v_fmac_f32_e32 v87, v86, v86
	v_mul_f32_e32 v86, v89, v89
	v_lshlrev_b32_e32 v162, 16, v176
	v_and_b32_e32 v163, 0xffff0000, v176
	v_fmac_f32_e32 v86, v88, v88
	v_lshlrev_b32_e32 v164, 16, v177
	v_and_b32_e32 v165, 0xffff0000, v177
	v_add_f32_e32 v86, v87, v86
	v_pk_add_f32 v[78:79], v[78:79], v[162:163]
	v_cvt_pk_bf16_f32 v91, v88, v89
	v_add_f32_e32 v88, v92, v86
	v_pk_add_f32 v[80:81], v[80:81], v[164:165]
	v_cvt_pk_bf16_f32 v86, v78, v79
	v_mul_f32_e32 v79, v79, v79
	v_fmac_f32_e32 v79, v78, v78
	v_mul_f32_e32 v78, v81, v81
	v_lshl_add_u64 v[100:101], s[2:3], 0, v[154:155]
	v_fmac_f32_e32 v78, v80, v80
	v_lshlrev_b32_e32 v160, 16, v179
	v_and_b32_e32 v161, 0xffff0000, v179
	v_lshl_add_u64 v[100:101], v[100:101], 0, v[136:137]
	v_cvt_pk_bf16_f32 v87, v80, v81
	v_add_f32_e32 v78, v79, v78
	v_lshlrev_b32_e32 v158, 16, v178
	v_and_b32_e32 v159, 0xffff0000, v178
	v_lshlrev_b32_e32 v152, 16, v180
	v_and_b32_e32 v153, 0xffff0000, v180
	global_store_dwordx2 v[100:101], v[86:87], off offset:288
	v_add_f32_e32 v86, v88, v78
	v_pk_add_f32 v[78:79], v[84:85], v[160:161]
	v_lshlrev_b32_e32 v156, 16, v181
	v_and_b32_e32 v157, 0xffff0000, v181
	v_pk_add_f32 v[80:81], v[82:83], v[158:159]
	v_cvt_pk_bf16_f32 v83, v78, v79
	v_mul_f32_e32 v79, v79, v79
	v_pk_add_f32 v[74:75], v[74:75], v[152:153]
	v_fmac_f32_e32 v79, v78, v78
	v_pk_add_f32 v[76:77], v[76:77], v[156:157]
	v_cvt_pk_bf16_f32 v78, v74, v75
	v_mul_f32_e32 v75, v75, v75
	v_cvt_pk_bf16_f32 v82, v80, v81
	v_mul_f32_e32 v81, v81, v81
	v_fmac_f32_e32 v75, v74, v74
	v_mul_f32_e32 v74, v77, v77
	v_lshlrev_b32_e32 v148, 16, v182
	v_and_b32_e32 v149, 0xffff0000, v182
	v_fmac_f32_e32 v81, v80, v80
	v_fmac_f32_e32 v74, v76, v76
	v_lshlrev_b32_e32 v150, 16, v183
	v_and_b32_e32 v151, 0xffff0000, v183
	v_add_f32_e32 v80, v81, v79
	v_add_f32_e32 v74, v75, v74
	v_pk_add_f32 v[70:71], v[70:71], v[148:149]
	v_cvt_pk_bf16_f32 v79, v76, v77
	v_add_f32_e32 v76, v80, v74
	v_pk_add_f32 v[72:73], v[72:73], v[150:151]
	v_cvt_pk_bf16_f32 v74, v70, v71
	v_mul_f32_e32 v71, v71, v71
	v_fmac_f32_e32 v71, v70, v70
	v_mul_f32_e32 v70, v73, v73
	v_fmac_f32_e32 v70, v72, v72
	v_add_f32_e32 v70, v71, v70
	v_pk_add_f32 v[66:67], v[66:67], v[144:145]
	v_cvt_pk_bf16_f32 v75, v72, v73
	v_add_f32_e32 v72, v76, v70
	v_pk_add_f32 v[68:69], v[68:69], v[146:147]
	v_cvt_pk_bf16_f32 v70, v66, v67
	v_mul_f32_e32 v67, v67, v67
	v_fmac_f32_e32 v67, v66, v66
	v_mul_f32_e32 v66, v69, v69
	v_fmac_f32_e32 v66, v68, v68
	v_lshl_add_u64 v[84:85], s[2:3], 0, v[142:143]
	v_add_f32_e32 v66, v67, v66
	v_lshl_add_u64 v[84:85], v[84:85], 0, v[136:137]
	v_cvt_pk_bf16_f32 v71, v68, v69
	v_add_f32_e32 v66, v72, v66
	global_store_dwordx2 v[84:85], v[70:71], off offset:288
	v_mov_b32_e32 v67, v118
	v_mov_b32_e32 v68, v102
	v_mov_b32_e32 v69, v86
	v_mov_b32_e32 v70, v66
	v_permlane16_swap_b32_e32 v118, v67
	v_permlane16_swap_b32_e32 v102, v68
	v_permlane16_swap_b32_e32 v86, v69
	v_permlane16_swap_b32_e32 v66, v70
	v_add_f32_e32 v67, v118, v67
	v_add_f32_e32 v68, v102, v68
	v_add_f32_e32 v69, v86, v69
	v_add_f32_e32 v71, v66, v70
	global_store_dwordx2 v[84:85], v[74:75], off offset:256
	v_mov_b32_e32 v70, v67
	v_mov_b32_e32 v72, v68
	v_mov_b32_e32 v73, v69
	v_mov_b32_e32 v74, v71
	v_permlane32_swap_b32_e32 v67, v70
	v_permlane32_swap_b32_e32 v68, v72
	v_permlane32_swap_b32_e32 v69, v73
	v_permlane32_swap_b32_e32 v71, v74
	v_add_u32_e32 v66, s14, v141
	global_store_dwordx2 v[168:169], v[174:175], off
	global_store_dwordx2 v[168:169], v[126:127], off offset:32
	global_store_dwordx2 v[168:169], v[122:123], off offset:256
	global_store_dwordx2 v[116:117], v[114:115], off
	global_store_dwordx2 v[116:117], v[110:111], off offset:32
	global_store_dwordx2 v[116:117], v[106:107], off offset:256
	global_store_dwordx2 v[100:101], v[98:99], off
	global_store_dwordx2 v[100:101], v[94:95], off offset:32
	global_store_dwordx2 v[100:101], v[90:91], off offset:256
	global_store_dwordx2 v[84:85], v[82:83], off
	global_store_dwordx2 v[84:85], v[78:79], off offset:32
	s_and_saveexec_b64 s[14:15], vcc
	s_cbranch_execz .LBB0_1347
	s_lshl_b32 s16, s40, 2
	s_ashr_i32 s17, s16, 31
	s_lshl_b64 s[16:17], s[16:17], 2
	s_add_u32 s16, s34, s16
	v_add_f32_e32 v70, v67, v70
	v_ashrrev_i32_e32 v67, 31, v66
	s_addc_u32 s17, s35, s17
	v_add_f32_e32 v73, v69, v73
	v_add_f32_e32 v72, v68, v72
	v_lshlrev_b64 v[68:69], 6, v[66:67]
	v_lshl_add_u64 v[68:69], s[16:17], 0, v[68:69]
	global_store_dword v[68:69], v70, off
	v_or_b32_e32 v68, 16, v66
	v_ashrrev_i32_e32 v69, 31, v68
	v_lshlrev_b64 v[68:69], 6, v[68:69]
	v_lshl_add_u64 v[68:69], s[16:17], 0, v[68:69]
	global_store_dword v[68:69], v72, off
	v_or_b32_e32 v68, 32, v66
	v_ashrrev_i32_e32 v69, 31, v68
	v_lshlrev_b64 v[68:69], 6, v[68:69]
	v_lshl_add_u64 v[68:69], s[16:17], 0, v[68:69]
	global_store_dword v[68:69], v73, off
	v_or_b32_e32 v68, 48, v66
	v_ashrrev_i32_e32 v69, 31, v68
	v_lshlrev_b64 v[68:69], 6, v[68:69]
	v_add_f32_e32 v71, v71, v74
	v_lshl_add_u64 v[68:69], s[16:17], 0, v[68:69]
	global_store_dword v[68:69], v71, off
.LBB0_1347:
	s_or_b64 exec, exec, s[14:15]
	v_add_u32_e32 v68, 0x80, v140
	v_ashrrev_i32_e32 v69, 31, v68
	v_add_u32_e32 v76, 0x90, v140
	v_lshlrev_b64 v[92:93], 11, v[68:69]
	v_ashrrev_i32_e32 v77, 31, v76
	v_add_u32_e32 v80, 0xa0, v140
	v_lshl_add_u64 v[68:69], v[138:139], 0, v[92:93]
	v_lshlrev_b64 v[94:95], 11, v[76:77]
	v_ashrrev_i32_e32 v81, 31, v80
	v_lshl_add_u64 v[68:69], v[138:139], 0, v[94:95]
	v_lshlrev_b64 v[80:81], 11, v[80:81]
	v_add_u32_e32 v98, 0xb0, v140
	v_lshl_add_u64 v[68:69], v[138:139], 0, v[80:81]
	v_ashrrev_i32_e32 v99, 31, v98
	v_lshlrev_b64 v[68:69], 11, v[98:99]
	v_lshl_add_u64 v[98:99], v[138:139], 0, v[68:69]
	v_lshl_add_u64 v[92:93], s[2:3], 0, v[92:93]
	v_lshl_add_u64 v[92:93], v[92:93], 0, v[136:137]
	s_waitcnt vmcnt(15)
	v_lshlrev_b32_e32 v108, 16, v250
	v_and_b32_e32 v109, 0xffff0000, v250
	v_lshlrev_b32_e32 v110, 16, v251
	v_and_b32_e32 v111, 0xffff0000, v251
	v_pk_add_f32 v[62:63], v[62:63], v[108:109]
	v_pk_add_f32 v[64:65], v[64:65], v[110:111]
	v_lshlrev_b32_e32 v112, 16, v248
	v_and_b32_e32 v113, 0xffff0000, v248
	v_lshlrev_b32_e32 v114, 16, v249
	v_and_b32_e32 v115, 0xffff0000, v249
	v_pk_add_f32 v[58:59], v[58:59], v[112:113]
	v_pk_add_f32 v[60:61], v[60:61], v[114:115]
	v_lshlrev_b32_e32 v116, 16, v246
	v_and_b32_e32 v117, 0xffff0000, v246
	v_lshlrev_b32_e32 v118, 16, v247
	v_lshlrev_b32_e32 v70, 16, v184
	v_and_b32_e32 v71, 0xffff0000, v184
	v_cvt_pk_bf16_f32 v98, v62, v63
	v_mul_f32_e32 v63, v63, v63
	v_fmac_f32_e32 v63, v62, v62
	v_mul_f32_e32 v62, v65, v65
	v_fmac_f32_e32 v62, v64, v64
	v_lshlrev_b32_e32 v72, 16, v185
	v_and_b32_e32 v73, 0xffff0000, v185
	v_cvt_pk_bf16_f32 v99, v64, v65
	v_add_f32_e32 v64, v63, v62
	v_cvt_pk_bf16_f32 v62, v58, v59
	v_mul_f32_e32 v59, v59, v59
	v_fmac_f32_e32 v59, v58, v58
	v_mul_f32_e32 v58, v61, v61
	v_fmac_f32_e32 v58, v60, v60
	v_and_b32_e32 v119, 0xffff0000, v247
	v_add_f32_e32 v58, v59, v58
	v_pk_add_f32 v[54:55], v[54:55], v[116:117]
	v_cvt_pk_bf16_f32 v63, v60, v61
	v_add_f32_e32 v60, v64, v58
	v_pk_add_f32 v[56:57], v[56:57], v[118:119]
	v_cvt_pk_bf16_f32 v58, v54, v55
	v_mul_f32_e32 v55, v55, v55
	v_fmac_f32_e32 v55, v54, v54
	v_mul_f32_e32 v54, v57, v57
	v_lshlrev_b32_e32 v120, 16, v244
	v_and_b32_e32 v121, 0xffff0000, v244
	v_fmac_f32_e32 v54, v56, v56
	v_lshlrev_b32_e32 v122, 16, v245
	v_and_b32_e32 v123, 0xffff0000, v245
	v_add_f32_e32 v54, v55, v54
	v_pk_add_f32 v[46:47], v[46:47], v[120:121]
	v_cvt_pk_bf16_f32 v59, v56, v57
	v_add_f32_e32 v56, v60, v54
	v_pk_add_f32 v[48:49], v[48:49], v[122:123]
	v_cvt_pk_bf16_f32 v54, v46, v47
	v_mul_f32_e32 v47, v47, v47
	v_fmac_f32_e32 v47, v46, v46
	v_mul_f32_e32 v46, v49, v49
	v_fmac_f32_e32 v46, v48, v48
	v_lshlrev_b32_e32 v126, 16, v243
	v_and_b32_e32 v127, 0xffff0000, v243
	v_cvt_pk_bf16_f32 v55, v48, v49
	v_add_f32_e32 v46, v47, v46
	v_lshlrev_b32_e32 v124, 16, v242
	v_and_b32_e32 v125, 0xffff0000, v242
	v_lshlrev_b32_e32 v128, 16, v240
	v_and_b32_e32 v129, 0xffff0000, v240
	global_store_dwordx2 v[92:93], v[54:55], off offset:288
	v_add_f32_e32 v54, v56, v46
	v_pk_add_f32 v[46:47], v[52:53], v[126:127]
	v_lshlrev_b32_e32 v138, 16, v241
	v_and_b32_e32 v139, 0xffff0000, v241
	v_pk_add_f32 v[48:49], v[50:51], v[124:125]
	v_cvt_pk_bf16_f32 v51, v46, v47
	v_mul_f32_e32 v47, v47, v47
	v_pk_add_f32 v[42:43], v[42:43], v[128:129]
	v_fmac_f32_e32 v47, v46, v46
	v_pk_add_f32 v[44:45], v[44:45], v[138:139]
	v_cvt_pk_bf16_f32 v46, v42, v43
	v_mul_f32_e32 v43, v43, v43
	v_cvt_pk_bf16_f32 v50, v48, v49
	v_mul_f32_e32 v49, v49, v49
	v_fmac_f32_e32 v43, v42, v42
	v_mul_f32_e32 v42, v45, v45
	v_lshlrev_b32_e32 v140, 16, v238
	v_and_b32_e32 v141, 0xffff0000, v238
	v_fmac_f32_e32 v49, v48, v48
	v_fmac_f32_e32 v42, v44, v44
	v_lshlrev_b32_e32 v142, 16, v239
	v_and_b32_e32 v143, 0xffff0000, v239
	v_add_f32_e32 v48, v49, v47
	v_add_f32_e32 v42, v43, v42
	v_pk_add_f32 v[38:39], v[38:39], v[140:141]
	v_cvt_pk_bf16_f32 v47, v44, v45
	v_add_f32_e32 v44, v48, v42
	v_pk_add_f32 v[40:41], v[40:41], v[142:143]
	v_cvt_pk_bf16_f32 v42, v38, v39
	v_mul_f32_e32 v39, v39, v39
	v_fmac_f32_e32 v39, v38, v38
	v_mul_f32_e32 v38, v41, v41
	v_lshlrev_b32_e32 v144, 16, v236
	v_and_b32_e32 v145, 0xffff0000, v236
	v_fmac_f32_e32 v38, v40, v40
	v_lshlrev_b32_e32 v146, 16, v237
	v_and_b32_e32 v147, 0xffff0000, v237
	v_add_f32_e32 v38, v39, v38
	v_pk_add_f32 v[30:31], v[30:31], v[144:145]
	v_cvt_pk_bf16_f32 v43, v40, v41
	v_add_f32_e32 v40, v44, v38
	v_pk_add_f32 v[32:33], v[32:33], v[146:147]
	v_cvt_pk_bf16_f32 v38, v30, v31
	v_mul_f32_e32 v31, v31, v31
	v_fmac_f32_e32 v31, v30, v30
	v_mul_f32_e32 v30, v33, v33
	v_lshl_add_u64 v[52:53], s[2:3], 0, v[94:95]
	v_fmac_f32_e32 v30, v32, v32
	v_lshlrev_b32_e32 v150, 16, v199
	v_and_b32_e32 v151, 0xffff0000, v199
	v_lshl_add_u64 v[52:53], v[52:53], 0, v[136:137]
	v_cvt_pk_bf16_f32 v39, v32, v33
	v_add_f32_e32 v30, v31, v30
	v_lshlrev_b32_e32 v148, 16, v198
	v_and_b32_e32 v149, 0xffff0000, v198
	v_lshlrev_b32_e32 v152, 16, v196
	v_and_b32_e32 v153, 0xffff0000, v196
	global_store_dwordx2 v[52:53], v[38:39], off offset:288
	v_add_f32_e32 v38, v40, v30
	v_pk_add_f32 v[30:31], v[36:37], v[150:151]
	v_lshlrev_b32_e32 v154, 16, v197
	v_and_b32_e32 v155, 0xffff0000, v197
	v_pk_add_f32 v[32:33], v[34:35], v[148:149]
	v_cvt_pk_bf16_f32 v35, v30, v31
	v_mul_f32_e32 v31, v31, v31
	v_pk_add_f32 v[26:27], v[26:27], v[152:153]
	v_fmac_f32_e32 v31, v30, v30
	v_pk_add_f32 v[28:29], v[28:29], v[154:155]
	v_cvt_pk_bf16_f32 v30, v26, v27
	v_mul_f32_e32 v27, v27, v27
	v_cvt_pk_bf16_f32 v34, v32, v33
	v_mul_f32_e32 v33, v33, v33
	v_fmac_f32_e32 v27, v26, v26
	v_mul_f32_e32 v26, v29, v29
	v_lshlrev_b32_e32 v156, 16, v194
	v_and_b32_e32 v157, 0xffff0000, v194
	v_fmac_f32_e32 v33, v32, v32
	v_fmac_f32_e32 v26, v28, v28
	v_lshlrev_b32_e32 v96, 16, v195
	v_and_b32_e32 v97, 0xffff0000, v195
	v_add_f32_e32 v32, v33, v31
	v_add_f32_e32 v26, v27, v26
	v_pk_add_f32 v[22:23], v[22:23], v[156:157]
	v_cvt_pk_bf16_f32 v31, v28, v29
	v_add_f32_e32 v28, v32, v26
	v_pk_add_f32 v[24:25], v[24:25], v[96:97]
	v_cvt_pk_bf16_f32 v26, v22, v23
	v_mul_f32_e32 v23, v23, v23
	v_fmac_f32_e32 v23, v22, v22
	v_mul_f32_e32 v22, v25, v25
	v_lshlrev_b32_e32 v88, 16, v192
	v_and_b32_e32 v89, 0xffff0000, v192
	v_fmac_f32_e32 v22, v24, v24
	v_lshlrev_b32_e32 v90, 16, v193
	v_and_b32_e32 v91, 0xffff0000, v193
	v_add_f32_e32 v22, v23, v22
	v_pk_add_f32 v[14:15], v[14:15], v[88:89]
	v_cvt_pk_bf16_f32 v27, v24, v25
	v_add_f32_e32 v24, v28, v22
	v_pk_add_f32 v[16:17], v[16:17], v[90:91]
	v_cvt_pk_bf16_f32 v22, v14, v15
	v_mul_f32_e32 v15, v15, v15
	v_fmac_f32_e32 v15, v14, v14
	v_mul_f32_e32 v14, v17, v17
	v_lshl_add_u64 v[36:37], s[2:3], 0, v[80:81]
	v_fmac_f32_e32 v14, v16, v16
	v_lshlrev_b32_e32 v86, 16, v191
	v_and_b32_e32 v87, 0xffff0000, v191
	v_lshl_add_u64 v[36:37], v[36:37], 0, v[136:137]
	v_cvt_pk_bf16_f32 v23, v16, v17
	v_add_f32_e32 v14, v15, v14
	v_lshlrev_b32_e32 v84, 16, v190
	v_and_b32_e32 v85, 0xffff0000, v190
	v_lshlrev_b32_e32 v78, 16, v188
	v_and_b32_e32 v79, 0xffff0000, v188
	global_store_dwordx2 v[36:37], v[22:23], off offset:288
	v_add_f32_e32 v22, v24, v14
	v_pk_add_f32 v[14:15], v[20:21], v[86:87]
	v_lshlrev_b32_e32 v82, 16, v189
	v_and_b32_e32 v83, 0xffff0000, v189
	v_pk_add_f32 v[16:17], v[18:19], v[84:85]
	v_cvt_pk_bf16_f32 v19, v14, v15
	v_mul_f32_e32 v15, v15, v15
	v_pk_add_f32 v[10:11], v[10:11], v[78:79]
	v_fmac_f32_e32 v15, v14, v14
	v_pk_add_f32 v[12:13], v[12:13], v[82:83]
	v_cvt_pk_bf16_f32 v14, v10, v11
	v_mul_f32_e32 v11, v11, v11
	v_cvt_pk_bf16_f32 v18, v16, v17
	v_mul_f32_e32 v17, v17, v17
	v_fmac_f32_e32 v11, v10, v10
	v_mul_f32_e32 v10, v13, v13
	v_lshlrev_b32_e32 v74, 16, v186
	v_and_b32_e32 v75, 0xffff0000, v186
	v_fmac_f32_e32 v17, v16, v16
	v_fmac_f32_e32 v10, v12, v12
	v_lshlrev_b32_e32 v76, 16, v187
	v_and_b32_e32 v77, 0xffff0000, v187
	v_add_f32_e32 v16, v17, v15
	v_add_f32_e32 v10, v11, v10
	v_pk_add_f32 v[6:7], v[6:7], v[74:75]
	v_cvt_pk_bf16_f32 v15, v12, v13
	v_add_f32_e32 v12, v16, v10
	v_pk_add_f32 v[8:9], v[8:9], v[76:77]
	v_cvt_pk_bf16_f32 v10, v6, v7
	v_mul_f32_e32 v7, v7, v7
	v_fmac_f32_e32 v7, v6, v6
	v_mul_f32_e32 v6, v9, v9
	v_fmac_f32_e32 v6, v8, v8
	v_add_f32_e32 v6, v7, v6
	v_pk_add_f32 v[2:3], v[2:3], v[70:71]
	v_cvt_pk_bf16_f32 v11, v8, v9
	v_add_f32_e32 v8, v12, v6
	v_pk_add_f32 v[4:5], v[4:5], v[72:73]
	v_cvt_pk_bf16_f32 v6, v2, v3
	v_mul_f32_e32 v3, v3, v3
	v_fmac_f32_e32 v3, v2, v2
	v_mul_f32_e32 v2, v5, v5
	v_fmac_f32_e32 v2, v4, v4
	v_lshl_add_u64 v[20:21], s[2:3], 0, v[68:69]
	v_add_f32_e32 v2, v3, v2
	v_lshl_add_u64 v[20:21], v[20:21], 0, v[136:137]
	v_cvt_pk_bf16_f32 v7, v4, v5
	v_add_f32_e32 v5, v8, v2
	global_store_dwordx2 v[20:21], v[6:7], off offset:288
	v_mov_b32_e32 v2, v54
	v_mov_b32_e32 v3, v38
	v_mov_b32_e32 v4, v22
	v_mov_b32_e32 v6, v5
	v_permlane16_swap_b32_e32 v54, v2
	v_permlane16_swap_b32_e32 v38, v3
	v_permlane16_swap_b32_e32 v22, v4
	v_permlane16_swap_b32_e32 v5, v6
	v_add_f32_e32 v2, v54, v2
	v_add_f32_e32 v3, v38, v3
	v_add_f32_e32 v4, v22, v4
	v_add_f32_e32 v6, v5, v6
	v_mov_b32_e32 v5, v2
	v_mov_b32_e32 v7, v3
	v_mov_b32_e32 v8, v4
	v_mov_b32_e32 v9, v6
	v_permlane32_swap_b32_e32 v2, v5
	v_permlane32_swap_b32_e32 v3, v7
	v_permlane32_swap_b32_e32 v4, v8
	v_permlane32_swap_b32_e32 v6, v9
	global_store_dwordx2 v[92:93], v[98:99], off
	global_store_dwordx2 v[92:93], v[62:63], off offset:32
	global_store_dwordx2 v[92:93], v[58:59], off offset:256
	global_store_dwordx2 v[52:53], v[50:51], off
	global_store_dwordx2 v[52:53], v[46:47], off offset:32
	global_store_dwordx2 v[52:53], v[42:43], off offset:256
	global_store_dwordx2 v[36:37], v[34:35], off
	global_store_dwordx2 v[36:37], v[30:31], off offset:32
	global_store_dwordx2 v[36:37], v[26:27], off offset:256
	global_store_dwordx2 v[20:21], v[18:19], off
	global_store_dwordx2 v[20:21], v[14:15], off offset:32
	global_store_dwordx2 v[20:21], v[10:11], off offset:256
	s_and_saveexec_b64 s[14:15], vcc
	s_cbranch_execz .LBB0_1349
	s_lshl_b32 s16, s40, 2
	s_ashr_i32 s17, s16, 31
	s_lshl_b64 s[16:17], s[16:17], 2
	v_add_u32_e32 v10, 0x80, v66
	s_add_u32 s16, s34, s16
	v_ashrrev_i32_e32 v11, 31, v10
	s_addc_u32 s17, s35, s17
	v_add_f32_e32 v7, v3, v7
	v_add_f32_e32 v5, v2, v5
	v_lshlrev_b64 v[2:3], 6, v[10:11]
	v_lshl_add_u64 v[2:3], s[16:17], 0, v[2:3]
	global_store_dword v[2:3], v5, off
	v_add_u32_e32 v2, 0x90, v66
	v_ashrrev_i32_e32 v3, 31, v2
	v_lshlrev_b64 v[2:3], 6, v[2:3]
	v_lshl_add_u64 v[2:3], s[16:17], 0, v[2:3]
	global_store_dword v[2:3], v7, off
	v_add_u32_e32 v2, 0xa0, v66
	v_ashrrev_i32_e32 v3, 31, v2
	v_lshlrev_b64 v[2:3], 6, v[2:3]
	v_add_f32_e32 v4, v4, v8
	v_lshl_add_u64 v[2:3], s[16:17], 0, v[2:3]
	global_store_dword v[2:3], v4, off
	v_add_u32_e32 v2, 0xb0, v66
	v_ashrrev_i32_e32 v3, 31, v2
	v_lshlrev_b64 v[2:3], 6, v[2:3]
	v_add_f32_e32 v6, v6, v9
	v_lshl_add_u64 v[2:3], s[16:17], 0, v[2:3]
	global_store_dword v[2:3], v6, off
